# code placement: in-proj GEMM K-loop head pinned back to its baseline 64-byte phase (6 s_nop at the phase entry)
# baseline (speedup 1.0000x reference)
; __device__ __forceinline__ int ltid() { int t = threadIdx.x; asm volatile("" : "+v"(t)); return t; }
;     __device__ __forceinline__ int begin(const Unit& u) const { return rsc.begin(u); }
;     __device__ __forceinline__ int begin(const Unit& u) const { return rsc.begin(u); }
;     __device__ __forceinline__ int begin(const Unit& u) const {
;         const int t = ltid();
;         if (t < BM) { float v[8];
; #pragma unroll
;             for (int p = 0; p < 8; ++p) v[p] = rsq[(size_t)(p < nparts ? p : 0) * mtot + u.pm * BM + t];
;             float s = v[0];
; #pragma unroll
;             for (int p = 1; p < 8; ++p) s += (p < nparts) ? v[p] : 0.f;
;             tab[t] = s; }
;         asm volatile("s_waitcnt lgkmcnt(0)\n\ts_barrier" ::: "memory");
.LBB0_424:
	s_andn2_b64 vcc, exec, s[0:1]
	s_cbranch_vccnz .LBB0_571
	s_cmp_gt_i32 s5, -1
	s_mov_b64 s[0:1], -1
	s_cbranch_scc0 .LBB0_515
	s_nop 0
	s_nop 0
	s_nop 0
	s_nop 0
	s_nop 0
	s_nop 0
	v_readlane_b32 s0, v255, 15
	s_mov_b64 s[8:9], s[92:93]
	v_mov_b32_e32 v1, v218
	v_mov_b32_e32 v10, v218
	v_readlane_b32 s1, v255, 16
	s_andn2_b64 vcc, exec, s[0:1]
	v_readfirstlane_b32 s20, v10
	s_cbranch_vccnz .LBB0_514
	s_load_dwordx2 s[0:1], s[8:9], 0x88
	v_mov_b32_e32 v2, v218
	s_nop 0
	v_cmp_gt_i32_e32 vcc, s89, v2
	s_and_saveexec_b64 s[10:11], vcc
	s_cbranch_execz .LBB0_429
	s_add_i32 s6, s64, -8
	s_cmp_lt_u32 s6, -13
	s_cselect_b64 vcc, -1, 0
	s_and_b64 s[6:7], vcc, exec
	s_cselect_b32 s86, 0x40000, 0
	s_cselect_b32 s12, 0x10000, 0
	s_waitcnt lgkmcnt(0)
	s_cselect_b32 s14, 0x20000, 0
	s_cselect_b32 s16, 0x30000, 0
	s_cselect_b32 s18, 0x50000, 0
	s_cselect_b32 s22, 0x60000, 0
	s_cselect_b32 s24, 0x70000, 0
	s_lshl_b32 s6, s86, 2
	s_add_u32 s6, s0, s6
	s_addc_u32 s7, s1, 0
	v_readlane_b32 s26, v255, 34
	v_readlane_b32 s27, v255, 35
	s_add_u32 s6, s6, s26
	v_ashrrev_i32_e32 v3, 31, v2
	s_addc_u32 s7, s7, s27
	v_lshl_add_u64 v[4:5], v[2:3], 2, s[6:7]
	s_mov_b64 s[6:7], 0x500000
	v_lshl_add_u64 v[6:7], v[4:5], 0, s[6:7]
	s_mov_b32 s6, 0x500000
	s_mov_b32 s13, s87
	s_mov_b32 s15, s87
	s_mov_b32 s17, s87
	s_mov_b32 s19, s87
	s_mov_b32 s23, s87
	s_mov_b32 s25, s87
	v_add_co_u32_e64 v4, s[6:7], s6, v4
	v_lshl_add_u64 v[8:9], v[6:7], 0, s[12:13]
	v_lshl_add_u64 v[12:13], v[6:7], 0, s[14:15]
	v_lshl_add_u64 v[14:15], v[6:7], 0, s[16:17]
	v_lshl_add_u64 v[16:17], v[6:7], 0, s[86:87]
	v_lshl_add_u64 v[18:19], v[6:7], 0, s[18:19]
	v_lshl_add_u64 v[20:21], v[6:7], 0, s[22:23]
	v_lshl_add_u64 v[6:7], v[6:7], 0, s[24:25]
	v_addc_co_u32_e64 v5, s[6:7], 0, v5, s[6:7]
	global_load_dword v1, v[8:9], off
	global_load_dword v3, v[12:13], off
	s_nop 0
	global_load_dword v8, v[14:15], off
	global_load_dword v9, v[16:17], off
	global_load_dword v11, v[18:19], off
	global_load_dword v12, v[20:21], off
	s_nop 0
	global_load_dword v6, v[6:7], off
	s_nop 0
	global_load_dword v4, v[4:5], off
	v_lshl_add_u32 v2, v2, 2, 0
	s_mov_b32 s86, 0x80000
	v_add_u32_e32 v2, 0x22400, v2
	s_waitcnt vmcnt(0)
	v_cndmask_b32_e32 v1, 0, v1, vcc
	v_cndmask_b32_e32 v3, 0, v3, vcc
	v_cndmask_b32_e32 v5, 0, v8, vcc
	v_cndmask_b32_e32 v7, 0, v9, vcc
	v_cndmask_b32_e32 v8, 0, v11, vcc
	v_cndmask_b32_e32 v9, 0, v12, vcc
	v_cndmask_b32_e32 v6, 0, v6, vcc
	v_add_f32_e32 v1, v4, v1
	v_add_f32_e32 v1, v1, v3
	v_add_f32_e32 v1, v1, v5
	v_add_f32_e32 v1, v1, v7
	v_add_f32_e32 v1, v1, v8
	v_add_f32_e32 v1, v1, v9
	v_add_f32_e32 v1, v1, v6
	ds_write_b32 v2, v1
